# P6 W3B conversion items re-split in 4 stages (4 per wave on all filler WGs, +6 on cb>=224, +10 on cb>=240, 4 on the 32 WGs that had no filler work) on top of k3
# speedup vs baseline: 1.0073x; 1.0015x over previous
; #define GAS __attribute__((address_space(1)))
; #define LAS __attribute__((address_space(3)))
; #define SEAM(k) do { if (IN(k) && IN((k) + 1)) xcd_barrier(bar); } while (0)
; __device__ __forceinline__ void mod_item256(Frame& F, const Args& A, int cg, int k0, int nsteps, float* dst, int ldd, int dcol0, const float* bias) {
;     const int lane = F.lane, w = F.wave, n0 = 256 * cg + 32 * w, tid = F.tid;
;     LAS unsigned char* sb = F.lds + w * MODI_SB;
;     LAS unsigned char* la = F.lds + MODI_A_OFF;
;     const bf16* CS = (const bf16*)(A.ws + WS_CSI);
;     const int kp = lane >> 3, a8 = lane & 7, n4 = 4 * a8;
;     const GAS char* Wb = (const GAS char*)(A.in[I_WADA] + (size_t)k0 * MODW + n0);
;     const unsigned wlo = (unsigned)((2 * kp) * MODW + n4) * 4u;
;     const GAS char* Cb = (const GAS char*)CS + (size_t)(k0 / 32) * 9216;
;     const unsigned c1 = (unsigned)tid * 16u, c2 = (unsigned)(512 + (tid & 63)) * 16u;
; __global__ void __launch_bounds__(NWAVES * 64, 2) mk_fwd(Args args) {
;     ...
;         if (rep == 0) { const int left8 = ((M / 256) * (NQ8 / 256)) % F.G;
;             if (cb >= left8) { const int ir = cb - left8, ni = F.G - left8;
;                 mod_chunk_partials(F, args, 2, ir, ni); __syncthreads(); { const int rank = ir * NWAVES + F.wave, nw = ni * NWAVES; conv_job<JOB_W3B>(F, args, rank, nw); } } } } } SEAM(6);
.LBB0_528:
	s_movk_i32 s99, 0x2b00
	s_mov_b32 s101, 2
	s_abs_i32 s0, s33
	v_cvt_f32_u32_e32 v2, s0
	s_sub_i32 s1, 0, s0
	v_rcp_iflag_f32_e32 v2, v2
	s_nop 0
	v_mul_f32_e32 v2, 0x4f7ffffe, v2
	v_cvt_u32_f32_e32 v2, v2
	s_nop 0
	v_readfirstlane_b32 s2, v2
	s_mul_i32 s1, s1, s2
	s_mul_hi_u32 s1, s2, s1
	s_add_i32 s2, s2, s1
	s_mul_hi_u32 s1, s2, 0x120
	s_mul_i32 s1, s1, s0
	s_sub_i32 s1, 0x120, s1
	s_sub_i32 s2, s1, s0
	s_cmp_ge_u32 s1, s0
	s_cselect_b32 s1, s2, s1
	s_sub_i32 s2, s1, s0
	s_cmp_ge_u32 s1, s0
	s_cselect_b32 s0, s2, s1
	s_cmp_lt_i32 s50, s0
	s_cbranch_scc1 .Lq_classA
	s_sub_i32 s1, s50, s0
	s_sub_i32 s0, s33, s0
	s_mov_b64 s[92:93], s[58:59]
	s_cmpk_gt_i32 s1, 0xbf
	v_lshrrev_b32_e32 v160, 5, v162
	s_cbranch_scc1 .LBB0_548
	v_lshrrev_b32_e32 v3, 2, v162
	s_add_u32 s22, s30, 0x63700000
	v_readlane_b32 s2, v252, 38
	v_lshlrev_b32_e32 v161, 2, v162
	v_and_b32_e32 v4, 14, v3
	s_addc_u32 s23, s31, 0
	s_lshl_b32 s34, s2, 5
	v_and_b32_e32 v2, 28, v161
	v_mul_u32_u24_e32 v4, 0x9000, v4
	s_mulk_i32 s2, 0xa00
	v_or_b32_e32 v4, v4, v2
	s_add_u32 s54, s30, 0x38d00000
	v_lshrrev_b32_e32 v5, 1, v162
	v_lshlrev_b32_e32 v122, 2, v4
	s_addc_u32 s55, s31, 0
	s_add_i32 s2, s2, 0
	v_and_b32_e32 v4, 3, v0
	v_and_b32_e32 v5, 12, v5
	v_add_u32_e32 v5, s2, v5
	v_mul_u32_u24_e32 v10, 0x50, v2
	v_bitop3_b32 v2, v160, v4, 2 bitop3:0x36
	v_lshl_add_u32 v11, v2, 4, v5
	v_and_b32_e32 v2, 12, v3
	v_mul_u32_u24_e32 v128, 0xc000, v2
	v_or_b32_e32 v2, 3, v3
	v_mul_u32_u24_e32 v132, 0xc000, v2
	v_or_b32_e32 v2, 19, v3
	v_mul_u32_u24_e32 v134, 0xc000, v2
	v_or_b32_e32 v2, 35, v3
	v_mul_u32_u24_e32 v136, 0xc000, v2
	v_or_b32_e32 v2, 51, v3
	v_mul_u32_u24_e32 v138, 0xc000, v2
	v_or_b32_e32 v2, 0x43, v3
	v_mul_u32_u24_e32 v144, 0xc000, v2
	v_or_b32_e32 v2, 0x53, v3
	v_mul_u32_u24_e32 v146, 0xc000, v2
	v_or_b32_e32 v2, 0x63, v3
	v_mul_u32_u24_e32 v148, 0xc000, v2
	v_or_b32_e32 v2, 0x73, v3
	v_readlane_b32 s76, v252, 19
	v_bitop3_b32 v9, v160, v0, 3 bitop3:0x78
	v_mul_u32_u24_e32 v150, 0xc000, v2
	v_readlane_b32 s80, v252, 23
	v_readlane_b32 s81, v252, 24
	v_lshrrev_b32_e32 v13, 6, v0
	s_mov_b32 s58, 0x24000
	v_mov_b64_e32 v[2:3], s[30:31]
	v_lshl_add_u32 v9, v9, 4, v5
	s_add_u32 s72, s30, 0x50000
	v_readlane_b32 s82, v252, 25
	v_readlane_b32 s83, v252, 26
	v_readlane_b32 s84, v252, 27
	v_readlane_b32 s85, v252, 28
	v_readlane_b32 s86, v252, 29
	v_readlane_b32 s87, v252, 30
	v_readlane_b32 s88, v252, 31
	v_readlane_b32 s89, v252, 32
	v_readlane_b32 s90, v252, 33
	v_readlane_b32 s91, v252, 34
	s_mov_b64 s[40:41], s[80:81]
	v_mad_u64_u32 v[4:5], s[10:11], v13, s58, v[2:3]
	v_bitop3_b32 v7, v161, 48, v0 bitop3:0x48
	s_mov_b32 s6, 0xc000
	s_addc_u32 s73, s31, 0
	s_mov_b64 s[48:49], s[88:89]
	s_mov_b64 s[10:11], 0x38f18000
	v_and_b32_e32 v6, 0x3f0, v164
	v_mov_b32_e32 v165, 0
	v_add_u32_e32 v7, s2, v7
	v_lshlrev_b32_e32 v8, 4, v162
	v_mul_u32_u24_e32 v12, 0x50, v190
	v_readlane_b32 s77, v252, 20
	v_readlane_b32 s78, v252, 21
	v_readlane_b32 s79, v252, 22
	s_add_u32 s8, s48, 0x18000
	v_lshl_add_u64 v[154:155], v[4:5], 0, s[10:11]
	v_mad_u64_u32 v[156:157], s[10:11], v13, s6, v[2:3]
	v_or_b32_e32 v124, 0x2000, v6
	v_mov_b32_e32 v125, v165
	v_mov_b32_e32 v123, v165
	s_mov_b32 s7, 0
	v_or_b32_e32 v126, s34, v190
	v_mov_b32_e32 v127, v165
	v_mov_b32_e32 v129, v165
	v_or_b32_e32 v130, 0xc000, v128
	v_mov_b32_e32 v131, v165
	v_mov_b32_e32 v133, v165
	v_mov_b32_e32 v135, v165
	v_mov_b32_e32 v137, v165
	v_mov_b32_e32 v139, v165
	v_or_b32_e32 v140, 0x300000, v128
	v_mov_b32_e32 v141, v165
	v_or_b32_e32 v142, 0x30c000, v128
	v_mov_b32_e32 v143, v165
	v_mov_b32_e32 v145, v165
	v_mov_b32_e32 v147, v165
	v_mov_b32_e32 v149, v165
	v_mov_b32_e32 v151, v165
	v_cmp_gt_u32_e64 s[2:3], 16, v162
	v_or_b32_e32 v152, 0x600000, v128
	v_mov_b32_e32 v153, v165
	s_mov_b64 s[42:43], s[82:83]
	s_mov_b64 s[44:45], s[84:85]
	s_mov_b64 s[46:47], s[86:87]
	s_mov_b64 s[50:51], s[90:91]
	s_addc_u32 s9, s49, 0
	v_or_b32_e32 v166, 0xfffffe00, v0
	s_mov_b32 s59, 0x240000
	s_mov_b32 s74, 0x480000
	v_add_u32_e32 v167, v9, v10
	v_add_u32_e32 v168, v11, v10
	s_mov_b32 s75, 0x900000
	s_mov_b32 s76, 0x924000
	s_mov_b32 s77, 0xb40000
	s_mov_b32 s78, 0xb64000
	v_add_u32_e32 v169, v7, v12
	v_add_u32_e32 v170, 0, v8
	s_mov_b32 s79, 0x3d8000
	s_mov_b32 s84, 0x48c000
	s_mov_b32 s85, 0x498000
	s_mov_b32 s86, 0x540000
	s_add_i32 s87, 0, 0x23140
	s_mov_b64 s[10:11], 0x120000
	s_mov_b64 s[12:13], 0x60000
	s_movk_i32 s88, 0x1e3f
	v_add_u32_e32 v171, 0, v164
	v_add_u32_e32 v172, 0, v6
	s_mov_b32 s89, s1
	s_branch .LBB0_532

; #define SEAM(k) do { if (IN(k) && IN((k) + 1)) xcd_barrier(bar); } while (0)
; template <int JOB>
; __device__ __forceinline__ void conv_job(Frame& F, const Args& A, int rank, int nw) {
;     ...
;     for (int it = rank; it < N; it += nw) {
; __global__ void __launch_bounds__(NWAVES * 64, 2) mk_fwd(Args args) {
;     ...
;         if (rep == 0) { const int left8 = ((M / 256) * (NQ8 / 256)) % F.G;
;             if (cb >= left8) { const int ir = cb - left8, ni = F.G - left8;
;                 mod_chunk_partials(F, args, 2, ir, ni); __syncthreads(); { const int rank = ir * NWAVES + F.wave, nw = ni * NWAVES; conv_job<JOB_W3B>(F, args, rank, nw); } } } } } SEAM(6);
.LBB0_548:
	s_lshl_b32 s1, s1, 3
	v_readlane_b32 s2, v252, 38
	s_add_i32 s1, s1, s2
	s_mov_b32 s100, s1
	s_cmpk_eq_i32 s33, 0x100
	s_cbranch_scc0 .Lq_nosplit
	s_movk_i32 s99, 0x1c00
	s_mov_b32 s101, 0
	s_cmp_eq_u32 s98, 7
	s_cbranch_scc0 .Lq_nosplit
	s_movk_i32 s99, 0x2b00
	s_mov_b32 s101, 2
	s_mov_b32 s98, 2

; #define SEAM(k) do { if (IN(k) && IN((k) + 1)) xcd_barrier(bar); } while (0)
; template <int JOB>
; __device__ __forceinline__ void conv_job(Frame& F, const Args& A, int rank, int nw) {
;     ...
;     for (int it = rank; it < N; it += nw) {
; __global__ void __launch_bounds__(NWAVES * 64, 2) mk_fwd(Args args) {
;     ...
;         if (rep == 0) { const int left8 = ((M / 256) * (NQ8 / 256)) % F.G;
;             if (cb >= left8) { const int ir = cb - left8, ni = F.G - left8;
;                 mod_chunk_partials(F, args, 2, ir, ni); __syncthreads(); { const int rank = ir * NWAVES + F.wave, nw = ni * NWAVES; conv_job<JOB_W3B>(F, args, rank, nw); } } } } } SEAM(6);
.LBB0_551:
	s_cmp_eq_u32 s101, 0
	s_cbranch_scc1 .Lq_s1done
	s_cmp_eq_u32 s101, 1
	s_cbranch_scc1 .Lq_s2done
	s_branch .Lq_done
.Lq_s1done:
	s_mov_b32 s101, 1
	s_cmpk_lt_i32 s100, 0x600
	s_cbranch_scc1 .Lq_done
	s_add_i32 s1, s100, 0x1600
	s_movk_i32 s8, 0x100
	s_movk_i32 s0, 0x2000
	s_lshl_b32 s9, s1, 5
	s_movk_i32 s99, 0x2200
	s_branch .LBB0_550
.Lq_s2done:
	s_mov_b32 s101, 2
	s_cmpk_lt_i32 s100, 0x680
	s_cbranch_scc1 .Lq_done
	s_add_i32 s1, s100, 0x1b80
	s_movk_i32 s8, 0x80
	s_movk_i32 s0, 0x1000
	s_lshl_b32 s9, s1, 5
	s_movk_i32 s99, 0x2700
	s_branch .LBB0_550
.Lq_classA:
	s_cmpk_eq_i32 s33, 0x100
	s_cbranch_scc0 .Lq_done
	s_mov_b64 s[92:93], s[58:59]
	v_lshrrev_b32_e32 v160, 5, v162
	s_add_i32 s1, s50, 1248
	s_mov_b32 s0, 32
	s_mov_b32 s98, 7
	s_branch .LBB0_548
